# v8: P11 token-split overlap + counted vmcnt; P13 direct K prefetch; P2 batched Q loads + deep ds_read prefetch in S; P1 epilogue batched cos/sin loads
# speedup vs baseline: 1.0156x; 1.0035x over previous
;     __device__ __forceinline__ void operator()(const f32x4 (&acc)[2][2][4][2], const Unit& u, int wr, int wc, int fr, int fq) const {
;         const int sg = u.pn >> 3, cw = wc * 32 + 8 * fq, hd0 = (u.pn & 7) * 2; const bool rope = sg < 6;
;         const int dsh = 2 * (sg % 3);
;         const int row0 = u.pm * BM + wr * 64 + fr, f0 = 16 * wc + 4 * fq;
;         const int bb = u.pm >> 5;
;         const unsigned sbase = (unsigned)(((sg * 2 + bb) * 16 + hd0) * 8192) * 128u;
; #pragma unroll
;         for (int ai = 0; ai < 2; ++ai)
; #pragma unroll
;             for (int m = 0; m < 4; ++m) { const int row = row0 + ai * HALF + m * 16; const int si = row & 8191;
;                 const int rl = (si & ((1 << dsh) - 1)) * (8192 >> dsh) + (si >> dsh);
;                 f32x4 c = {1.f, 1.f, 1.f, 1.f}, s = {0.f, 0.f, 0.f, 0.f};
;                 if (rope) { c = __builtin_bit_cast(f32x4, __builtin_amdgcn_raw_buffer_load_b128(cs, (row * 64 + f0) * 4, 0, 0)); s = __builtin_bit_cast(f32x4, __builtin_amdgcn_raw_buffer_load_b128(sn, (row * 64 + f0) * 4, 0, 0)); }
; #pragma unroll
;                 for (int bj = 0; bj < 2; ++bj) { f32x4 v0 = acc[ai][bj][m][0] * scl, v1 = acc[ai][bj][m][1] * scl;
;                     rope_pair(v0, v1, c, s);
;                     int w0 = __builtin_amdgcn_cvt_pk_fp8_f32(v0[0], v0[1], 0, false); w0 = __builtin_amdgcn_cvt_pk_fp8_f32(v0[2], v0[3], w0, true);
;                     int w1 = __builtin_amdgcn_cvt_pk_fp8_f32(v1[0], v1[1], 0, false); w1 = __builtin_amdgcn_cvt_pk_fp8_f32(v1[2], v1[3], w1, true);
;                     typedef unsigned u32x2_t __attribute__((ext_vector_type(2)));
;                     __builtin_amdgcn_raw_buffer_store_b64((u32x2_t){(unsigned)w0, (unsigned)w1}, o, rl * 128 + cw, (int)(sbase + (unsigned)bj * (8192u * 128u)), 0); } }
.LBB0_320:
	v_mov_b32_e32 v128, 0
	s_ashr_i32 s7, s28, 3
	v_mbcnt_lo_u32_b32 v128, -1, v128
	s_cmp_lt_i32 s7, 6
	v_mbcnt_hi_u32_b32 v129, -1, v128
	s_cselect_b64 s[30:31], -1, 0
	s_lshl_b32 s14, s6, 8
	s_add_i32 s14, s14, s47
	v_and_b32_e32 v128, -16, v129
	s_cmp_gt_i32 s7, 5
	v_and_or_b32 v165, v129, 15, s14
	v_add_u32_e32 v164, s51, v128
	v_mov_b32_e32 v128, 1.0
	v_mov_b32_e32 v132, 0
	v_mov_b32_e32 v134, 0
	v_mov_b32_e32 v135, 0
	v_mov_b32_e32 v136, 0
	v_mov_b32_e32 v137, 0
	v_mov_b32_e32 v138, 1.0
	v_mov_b32_e32 v139, 1.0
	v_mov_b32_e32 v140, 1.0
	v_mov_b32_e32 v141, 1.0
	s_cbranch_scc1 .Lp1e_defaults
	s_mov_b32 s14, s10
	s_mov_b32 s15, s11
	v_lshl_add_u32 v130, v165, 8, v164
	buffer_load_dwordx4 v[168:171], v130, s[8:11], 0 offen
	buffer_load_dwordx4 v[172:175], v130, s[12:15], 0 offen
	v_add_u32_e32 v233, 16, v165
	v_lshl_add_u32 v233, v233, 8, v164
	buffer_load_dwordx4 v[176:179], v233, s[8:11], 0 offen
	buffer_load_dwordx4 v[180:183], v233, s[12:15], 0 offen
	v_add_u32_e32 v234, 32, v165
	v_lshl_add_u32 v234, v234, 8, v164
	buffer_load_dwordx4 v[184:187], v234, s[8:11], 0 offen
	buffer_load_dwordx4 v[188:191], v234, s[12:15], 0 offen
	v_add_u32_e32 v235, 48, v165
	v_lshl_add_u32 v235, v235, 8, v164
	buffer_load_dwordx4 v[192:195], v235, s[8:11], 0 offen
	buffer_load_dwordx4 v[196:199], v235, s[12:15], 0 offen
	v_add_u32_e32 v236, 128, v165
	v_lshl_add_u32 v236, v236, 8, v164
	buffer_load_dwordx4 v[200:203], v236, s[8:11], 0 offen
	buffer_load_dwordx4 v[204:207], v236, s[12:15], 0 offen
	v_add_u32_e32 v237, 144, v165
	v_lshl_add_u32 v237, v237, 8, v164
	buffer_load_dwordx4 v[208:211], v237, s[8:11], 0 offen
	buffer_load_dwordx4 v[212:215], v237, s[12:15], 0 offen
	v_add_u32_e32 v238, 160, v165
	v_lshl_add_u32 v238, v238, 8, v164
	buffer_load_dwordx4 v[216:219], v238, s[8:11], 0 offen
	buffer_load_dwordx4 v[220:223], v238, s[12:15], 0 offen
	v_add_u32_e32 v239, 176, v165
	v_lshl_add_u32 v239, v239, 8, v164
	buffer_load_dwordx4 v[224:227], v239, s[8:11], 0 offen
	buffer_load_dwordx4 v[228:231], v239, s[12:15], 0 offen
.LBB0_322:
	s_mul_hi_i32 s15, s7, 0x55555556
	s_lshr_b32 s21, s15, 31
	s_add_i32 s15, s15, s21
	s_mul_i32 s15, s15, 3
	v_ashrrev_i32_e32 v129, 1, v129
	s_sub_i32 s15, s7, s15
	v_and_b32_e32 v129, -8, v129
	s_lshl_b32 s23, s15, 1
	v_add_u32_e32 v163, s48, v129
	s_lshl_b32 s35, -1, s23
	v_and_b32_e32 v129, 0x1fcf, v165
	s_lshr_b32 s21, 0x2000, s23
	v_bitop3_b32 v130, v165, s35, v159 bitop3:0x20
	v_lshrrev_b32_e32 v129, s23, v129
	v_pk_mul_f32 v[120:121], v[120:121], s[18:19] op_sel_hi:[1,0]
	v_mad_u32_u24 v129, v130, s21, v129
	v_pk_mul_f32 v[124:125], v[124:125], s[18:19] op_sel_hi:[1,0]
	s_waitcnt vmcnt(14)
	v_pk_mul_f32 v[130:131], v[120:121], v[172:173]
	v_pk_mul_f32 v[120:121], v[120:121], v[168:169]
	v_pk_fma_f32 v[130:131], v[124:125], v[168:169], v[130:131] neg_lo:[0,0,1] neg_hi:[0,0,1]
	v_pk_fma_f32 v[120:121], v[124:125], v[172:173], v[120:121]
	v_mov_b32_e32 v125, 0
	v_cvt_pk_fp8_f32 v125, v120, v121
	v_pk_mul_f32 v[122:123], v[122:123], s[18:19] op_sel_hi:[1,0]
	v_pk_mul_f32 v[126:127], v[126:127], s[18:19] op_sel_hi:[1,0]
	v_pk_mul_f32 v[120:121], v[122:123], v[170:171]
	v_pk_mul_f32 v[112:113], v[112:113], s[18:19] op_sel_hi:[1,0]
	v_pk_fma_f32 v[120:121], v[126:127], v[174:175], v[120:121]
	v_pk_mul_f32 v[116:117], v[116:117], s[18:19] op_sel_hi:[1,0]
	v_cvt_pk_fp8_f32 v125, v120, v121 op_sel:[0,0,1]
	v_pk_mul_f32 v[120:121], v[112:113], v[172:173]
	v_pk_mul_f32 v[112:113], v[112:113], v[168:169]
	v_mov_b32_e32 v124, 0
	v_pk_fma_f32 v[120:121], v[116:117], v[168:169], v[120:121] neg_lo:[0,0,1] neg_hi:[0,0,1]
	v_pk_fma_f32 v[112:113], v[116:117], v[172:173], v[112:113]
	v_mov_b32_e32 v116, 0
	v_mov_b32_e32 v117, 0
	v_cvt_pk_fp8_f32 v124, v130, v131
	v_cvt_pk_fp8_f32 v116, v120, v121
	v_cvt_pk_fp8_f32 v117, v112, v113
	v_pk_mul_f32 v[114:115], v[114:115], s[18:19] op_sel_hi:[1,0]
	s_lshr_b32 s6, s6, 1
	v_pk_mul_f32 v[142:143], v[122:123], v[174:175]
	v_pk_mul_f32 v[118:119], v[118:119], s[18:19] op_sel_hi:[1,0]
	v_pk_mul_f32 v[122:123], v[114:115], v[174:175]
	v_pk_mul_f32 v[112:113], v[114:115], v[170:171]
	s_lshl_b32 s14, s28, 1
	s_lshl_b32 s7, s7, 5
	s_and_b32 s6, s6, 0xff0
	v_pk_fma_f32 v[142:143], v[126:127], v[170:171], v[142:143] neg_lo:[0,0,1] neg_hi:[0,0,1]
	v_pk_fma_f32 v[122:123], v[118:119], v[170:171], v[122:123] neg_lo:[0,0,1] neg_hi:[0,0,1]
	v_pk_fma_f32 v[112:113], v[118:119], v[174:175], v[112:113]
	s_and_b32 s14, s14, 14
	s_add_i32 s6, s6, s7
	v_cvt_pk_fp8_f32 v124, v142, v143 op_sel:[0,0,1]
	v_cvt_pk_fp8_f32 v116, v122, v123 op_sel:[0,0,1]
	v_cvt_pk_fp8_f32 v117, v112, v113 op_sel:[0,0,1]
	s_or_b32 s6, s6, s14
	s_lshl_b32 s28, s6, 20
	v_lshl_add_u32 v129, v129, 7, v163
	s_or_b32 s34, s28, 0x100000
	v_cndmask_b32_e64 v113, 0, 1, s[30:31]
	buffer_store_dwordx2 v[124:125], v129, s[84:87], s28 offen
	buffer_store_dwordx2 v[116:117], v129, s[84:87], s34 offen
	v_or_b32_e32 v112, 16, v165
	v_cmp_ne_u32_e64 s[6:7], 1, v113
	s_andn2_b64 vcc, exec, s[30:31]
	v_mov_b32_e32 v133, 0
	v_mov_b32_e32 v134, 0
	v_mov_b32_e32 v135, 0
	v_mov_b32_e32 v129, 1.0
	v_mov_b32_e32 v130, 1.0
	v_mov_b32_e32 v131, 1.0
;     __device__ __forceinline__ void operator()(const f32x4 (&acc)[2][2][4][2], const Unit& u, int wr, int wc, int fr, int fq) const {
;     ...
;             for (int m = 0; m < 4; ++m) { const int row = row0 + ai * HALF + m * 16; const int si = row & 8191;
;                 const int rl = (si & ((1 << dsh) - 1)) * (8192 >> dsh) + (si >> dsh);
;                 f32x4 c = {1.f, 1.f, 1.f, 1.f}, s = {0.f, 0.f, 0.f, 0.f};
;                 if (rope) { c = __builtin_bit_cast(f32x4, __builtin_amdgcn_raw_buffer_load_b128(cs, (row * 64 + f0) * 4, 0, 0)); s = __builtin_bit_cast(f32x4, __builtin_amdgcn_raw_buffer_load_b128(sn, (row * 64 + f0) * 4, 0, 0)); }
; #pragma unroll
;                 for (int bj = 0; bj < 2; ++bj) { f32x4 v0 = acc[ai][bj][m][0] * scl, v1 = acc[ai][bj][m][1] * scl;
;                     rope_pair(v0, v1, c, s);
;                     int w0 = __builtin_amdgcn_cvt_pk_fp8_f32(v0[0], v0[1], 0, false); w0 = __builtin_amdgcn_cvt_pk_fp8_f32(v0[2], v0[3], w0, true);
;                     int w1 = __builtin_amdgcn_cvt_pk_fp8_f32(v1[0], v1[1], 0, false); w1 = __builtin_amdgcn_cvt_pk_fp8_f32(v1[2], v1[3], w1, true);
;                     typedef unsigned u32x2_t __attribute__((ext_vector_type(2)));
;                     __builtin_amdgcn_raw_buffer_store_b64((u32x2_t){(unsigned)w0, (unsigned)w1}, o, rl * 128 + cw, (int)(sbase + (unsigned)bj * (8192u * 128u)), 0); } }
.LBB0_324:
	s_not_b32 s30, s35
	v_and_b32_e32 v113, 0x1fdf, v112
	v_mov_b32_e32 v118, 0x1fdf
	v_pk_mul_f32 v[104:105], v[104:105], s[18:19] op_sel_hi:[1,0]
	v_bitop3_b32 v116, v112, s30, v118 bitop3:0x80
	v_lshrrev_b32_e32 v117, s23, v113
	v_pk_mul_f32 v[108:109], v[108:109], s[18:19] op_sel_hi:[1,0]
	s_waitcnt vmcnt(14)
	v_pk_mul_f32 v[112:113], v[104:105], v[180:181]
	v_pk_mul_f32 v[104:105], v[104:105], v[176:177]
	v_pk_fma_f32 v[112:113], v[108:109], v[176:177], v[112:113] neg_lo:[0,0,1] neg_hi:[0,0,1]
	v_pk_fma_f32 v[104:105], v[108:109], v[180:181], v[104:105]
	v_mov_b32_e32 v109, 0
	v_cvt_pk_fp8_f32 v109, v104, v105
	v_pk_mul_f32 v[106:107], v[106:107], s[18:19] op_sel_hi:[1,0]
	v_pk_mul_f32 v[110:111], v[110:111], s[18:19] op_sel_hi:[1,0]
	v_pk_mul_f32 v[104:105], v[106:107], v[178:179]
	v_pk_mul_f32 v[96:97], v[96:97], s[18:19] op_sel_hi:[1,0]
	v_pk_fma_f32 v[104:105], v[110:111], v[182:183], v[104:105]
	v_mov_b32_e32 v108, 0
	v_cvt_pk_fp8_f32 v109, v104, v105 op_sel:[0,0,1]
	v_pk_mul_f32 v[100:101], v[100:101], s[18:19] op_sel_hi:[1,0]
	v_pk_mul_f32 v[104:105], v[96:97], v[180:181]
	v_pk_mul_f32 v[96:97], v[96:97], v[176:177]
	v_cvt_pk_fp8_f32 v108, v112, v113
	v_pk_fma_f32 v[104:105], v[100:101], v[176:177], v[104:105] neg_lo:[0,0,1] neg_hi:[0,0,1]
	v_pk_fma_f32 v[96:97], v[100:101], v[180:181], v[96:97]
	v_mov_b32_e32 v100, 0
	v_mov_b32_e32 v101, 0
	v_cvt_pk_fp8_f32 v100, v104, v105
	v_cvt_pk_fp8_f32 v101, v96, v97
	v_pk_mul_f32 v[114:115], v[106:107], v[182:183]
	v_pk_mul_f32 v[98:99], v[98:99], s[18:19] op_sel_hi:[1,0]
	v_pk_fma_f32 v[114:115], v[110:111], v[178:179], v[114:115] neg_lo:[0,0,1] neg_hi:[0,0,1]
	v_pk_mul_f32 v[102:103], v[102:103], s[18:19] op_sel_hi:[1,0]
	v_pk_mul_f32 v[106:107], v[98:99], v[182:183]
	v_pk_mul_f32 v[96:97], v[98:99], v[178:179]
	v_cvt_pk_fp8_f32 v108, v114, v115 op_sel:[0,0,1]
	v_pk_fma_f32 v[106:107], v[102:103], v[178:179], v[106:107] neg_lo:[0,0,1] neg_hi:[0,0,1]
	v_pk_fma_f32 v[96:97], v[102:103], v[182:183], v[96:97]
	v_cvt_pk_fp8_f32 v100, v106, v107 op_sel:[0,0,1]
	v_cvt_pk_fp8_f32 v101, v96, v97 op_sel:[0,0,1]
	v_mad_u32_u24 v96, v116, s21, v117
	v_lshl_add_u32 v96, v96, 7, v163
	buffer_store_dwordx2 v[108:109], v96, s[84:87], s28 offen
	buffer_store_dwordx2 v[100:101], v96, s[84:87], s34 offen
	v_or_b32_e32 v97, 32, v165
	v_mov_b32_e32 v96, 1.0
	v_mov_b32_e32 v100, 0
	s_and_b64 vcc, exec, s[6:7]
	v_mov_b32_e32 v102, 0
	v_mov_b32_e32 v103, 0
	v_mov_b32_e32 v104, 0
	v_mov_b32_e32 v105, 0
	v_mov_b32_e32 v106, 1.0
	v_mov_b32_e32 v107, 1.0
	v_mov_b32_e32 v108, 1.0
	v_mov_b32_e32 v109, 1.0
.LBB0_326:
	v_and_b32_e32 v98, 0x1fef, v97
	v_pk_mul_f32 v[88:89], v[88:89], s[18:19] op_sel_hi:[1,0]
	v_lshrrev_b32_e32 v101, s23, v98
	v_pk_mul_f32 v[92:93], v[92:93], s[18:19] op_sel_hi:[1,0]
	s_waitcnt vmcnt(14)
	v_pk_mul_f32 v[98:99], v[88:89], v[188:189]
	v_pk_mul_f32 v[88:89], v[88:89], v[184:185]
	v_pk_fma_f32 v[98:99], v[92:93], v[184:185], v[98:99] neg_lo:[0,0,1] neg_hi:[0,0,1]
	v_pk_fma_f32 v[88:89], v[92:93], v[188:189], v[88:89]
	v_mov_b32_e32 v93, 0
	v_cvt_pk_fp8_f32 v93, v88, v89
	v_pk_mul_f32 v[90:91], v[90:91], s[18:19] op_sel_hi:[1,0]
	v_pk_mul_f32 v[94:95], v[94:95], s[18:19] op_sel_hi:[1,0]
	v_pk_mul_f32 v[88:89], v[90:91], v[186:187]
	v_pk_mul_f32 v[80:81], v[80:81], s[18:19] op_sel_hi:[1,0]
	v_pk_fma_f32 v[88:89], v[94:95], v[190:191], v[88:89]
	v_mov_b32_e32 v92, 0
	v_cvt_pk_fp8_f32 v93, v88, v89 op_sel:[0,0,1]
	v_pk_mul_f32 v[84:85], v[84:85], s[18:19] op_sel_hi:[1,0]
	v_pk_mul_f32 v[88:89], v[80:81], v[188:189]
	v_pk_mul_f32 v[80:81], v[80:81], v[184:185]
	v_cvt_pk_fp8_f32 v92, v98, v99
	v_pk_fma_f32 v[88:89], v[84:85], v[184:185], v[88:89] neg_lo:[0,0,1] neg_hi:[0,0,1]
	v_pk_fma_f32 v[80:81], v[84:85], v[188:189], v[80:81]
	v_mov_b32_e32 v84, 0
	v_mov_b32_e32 v85, 0
	v_cvt_pk_fp8_f32 v84, v88, v89
	v_cvt_pk_fp8_f32 v85, v80, v81
	v_pk_mul_f32 v[110:111], v[90:91], v[190:191]
	v_pk_mul_f32 v[82:83], v[82:83], s[18:19] op_sel_hi:[1,0]
	v_pk_fma_f32 v[110:111], v[94:95], v[186:187], v[110:111] neg_lo:[0,0,1] neg_hi:[0,0,1]
	v_pk_mul_f32 v[86:87], v[86:87], s[18:19] op_sel_hi:[1,0]
	v_pk_mul_f32 v[90:91], v[82:83], v[190:191]
	v_pk_mul_f32 v[80:81], v[82:83], v[186:187]
	v_mov_b32_e32 v112, 0x1fef
	v_cvt_pk_fp8_f32 v92, v110, v111 op_sel:[0,0,1]
	v_pk_fma_f32 v[90:91], v[86:87], v[186:187], v[90:91] neg_lo:[0,0,1] neg_hi:[0,0,1]
	v_pk_fma_f32 v[80:81], v[86:87], v[190:191], v[80:81]
	v_bitop3_b32 v97, v97, s30, v112 bitop3:0x80
	v_cvt_pk_fp8_f32 v84, v90, v91 op_sel:[0,0,1]
	v_cvt_pk_fp8_f32 v85, v80, v81 op_sel:[0,0,1]
	v_mad_u32_u24 v80, v97, s21, v101
	v_lshl_add_u32 v80, v80, 7, v163
	buffer_store_dwordx2 v[92:93], v80, s[84:87], s28 offen
	buffer_store_dwordx2 v[84:85], v80, s[84:87], s34 offen
	v_or_b32_e32 v80, 48, v165
	s_and_b64 vcc, exec, s[6:7]
	v_mov_b32_e32 v101, 0
	v_mov_b32_e32 v102, 0
	v_mov_b32_e32 v103, 0
	v_mov_b32_e32 v97, 1.0
	v_mov_b32_e32 v98, 1.0
	v_mov_b32_e32 v99, 1.0
;     __device__ __forceinline__ void operator()(const f32x4 (&acc)[2][2][4][2], const Unit& u, int wr, int wc, int fr, int fq) const {
;     ...
;             for (int m = 0; m < 4; ++m) { const int row = row0 + ai * HALF + m * 16; const int si = row & 8191;
;                 const int rl = (si & ((1 << dsh) - 1)) * (8192 >> dsh) + (si >> dsh);
;                 f32x4 c = {1.f, 1.f, 1.f, 1.f}, s = {0.f, 0.f, 0.f, 0.f};
;                 if (rope) { c = __builtin_bit_cast(f32x4, __builtin_amdgcn_raw_buffer_load_b128(cs, (row * 64 + f0) * 4, 0, 0)); s = __builtin_bit_cast(f32x4, __builtin_amdgcn_raw_buffer_load_b128(sn, (row * 64 + f0) * 4, 0, 0)); }
; #pragma unroll
;                 for (int bj = 0; bj < 2; ++bj) { f32x4 v0 = acc[ai][bj][m][0] * scl, v1 = acc[ai][bj][m][1] * scl;
;                     rope_pair(v0, v1, c, s);
;                     int w0 = __builtin_amdgcn_cvt_pk_fp8_f32(v0[0], v0[1], 0, false); w0 = __builtin_amdgcn_cvt_pk_fp8_f32(v0[2], v0[3], w0, true);
;                     int w1 = __builtin_amdgcn_cvt_pk_fp8_f32(v1[0], v1[1], 0, false); w1 = __builtin_amdgcn_cvt_pk_fp8_f32(v1[2], v1[3], w1, true);
;                     typedef unsigned u32x2_t __attribute__((ext_vector_type(2)));
;                     __builtin_amdgcn_raw_buffer_store_b64((u32x2_t){(unsigned)w0, (unsigned)w1}, o, rl * 128 + cw, (int)(sbase + (unsigned)bj * (8192u * 128u)), 0); } }
.LBB0_328:
	v_and_b32_e32 v81, 0x1fff, v80
	v_mov_b32_e32 v86, 0x1fff
	v_pk_mul_f32 v[72:73], v[72:73], s[18:19] op_sel_hi:[1,0]
	v_bitop3_b32 v84, v80, s30, v86 bitop3:0x80
	v_lshrrev_b32_e32 v85, s23, v81
	v_pk_mul_f32 v[76:77], v[76:77], s[18:19] op_sel_hi:[1,0]
	s_waitcnt vmcnt(14)
	v_pk_mul_f32 v[80:81], v[72:73], v[196:197]
	v_pk_mul_f32 v[72:73], v[72:73], v[192:193]
	v_pk_fma_f32 v[80:81], v[76:77], v[192:193], v[80:81] neg_lo:[0,0,1] neg_hi:[0,0,1]
	v_pk_fma_f32 v[72:73], v[76:77], v[196:197], v[72:73]
	v_mov_b32_e32 v77, 0
	v_cvt_pk_fp8_f32 v77, v72, v73
	v_pk_mul_f32 v[74:75], v[74:75], s[18:19] op_sel_hi:[1,0]
	v_pk_mul_f32 v[78:79], v[78:79], s[18:19] op_sel_hi:[1,0]
	v_pk_mul_f32 v[72:73], v[74:75], v[194:195]
	v_pk_mul_f32 v[64:65], v[64:65], s[18:19] op_sel_hi:[1,0]
	v_pk_fma_f32 v[72:73], v[78:79], v[198:199], v[72:73]
	v_mov_b32_e32 v76, 0
	v_cvt_pk_fp8_f32 v77, v72, v73 op_sel:[0,0,1]
	v_pk_mul_f32 v[68:69], v[68:69], s[18:19] op_sel_hi:[1,0]
	v_pk_mul_f32 v[72:73], v[64:65], v[196:197]
	v_pk_mul_f32 v[64:65], v[64:65], v[192:193]
	v_cvt_pk_fp8_f32 v76, v80, v81
	v_pk_fma_f32 v[72:73], v[68:69], v[192:193], v[72:73] neg_lo:[0,0,1] neg_hi:[0,0,1]
	v_pk_fma_f32 v[64:65], v[68:69], v[196:197], v[64:65]
	v_mov_b32_e32 v68, 0
	v_mov_b32_e32 v69, 0
	v_cvt_pk_fp8_f32 v68, v72, v73
	v_cvt_pk_fp8_f32 v69, v64, v65
	v_pk_mul_f32 v[82:83], v[74:75], v[198:199]
	v_pk_mul_f32 v[66:67], v[66:67], s[18:19] op_sel_hi:[1,0]
	v_pk_fma_f32 v[82:83], v[78:79], v[194:195], v[82:83] neg_lo:[0,0,1] neg_hi:[0,0,1]
	v_pk_mul_f32 v[70:71], v[70:71], s[18:19] op_sel_hi:[1,0]
	v_pk_mul_f32 v[74:75], v[66:67], v[198:199]
	v_pk_mul_f32 v[64:65], v[66:67], v[194:195]
	v_cvt_pk_fp8_f32 v76, v82, v83 op_sel:[0,0,1]
	v_pk_fma_f32 v[74:75], v[70:71], v[194:195], v[74:75] neg_lo:[0,0,1] neg_hi:[0,0,1]
	v_pk_fma_f32 v[64:65], v[70:71], v[198:199], v[64:65]
	v_cvt_pk_fp8_f32 v68, v74, v75 op_sel:[0,0,1]
	v_cvt_pk_fp8_f32 v69, v64, v65 op_sel:[0,0,1]
	v_mad_u32_u24 v64, v84, s21, v85
	v_lshl_add_u32 v64, v64, 7, v163
	buffer_store_dwordx2 v[76:77], v64, s[84:87], s28 offen
	buffer_store_dwordx2 v[68:69], v64, s[84:87], s34 offen
	v_add_u32_e32 v65, 0x80, v165
	v_mov_b32_e32 v64, 1.0
	v_mov_b32_e32 v68, 0
	s_and_b64 vcc, exec, s[6:7]
	v_mov_b32_e32 v70, 0
	v_mov_b32_e32 v71, 0
	v_mov_b32_e32 v72, 0
	v_mov_b32_e32 v73, 0
	v_mov_b32_e32 v74, 1.0
	v_mov_b32_e32 v75, 1.0
	v_mov_b32_e32 v76, 1.0
	v_mov_b32_e32 v77, 1.0
.LBB0_330:
	v_and_b32_e32 v66, 0x1fcf, v65
	v_pk_mul_f32 v[56:57], v[56:57], s[18:19] op_sel_hi:[1,0]
	v_lshrrev_b32_e32 v69, s23, v66
	v_pk_mul_f32 v[60:61], v[60:61], s[18:19] op_sel_hi:[1,0]
	s_waitcnt vmcnt(14)
	v_pk_mul_f32 v[66:67], v[56:57], v[204:205]
	v_pk_mul_f32 v[56:57], v[56:57], v[200:201]
	v_pk_fma_f32 v[66:67], v[60:61], v[200:201], v[66:67] neg_lo:[0,0,1] neg_hi:[0,0,1]
	v_pk_fma_f32 v[56:57], v[60:61], v[204:205], v[56:57]
	v_mov_b32_e32 v61, 0
	v_cvt_pk_fp8_f32 v61, v56, v57
	v_pk_mul_f32 v[58:59], v[58:59], s[18:19] op_sel_hi:[1,0]
	v_pk_mul_f32 v[62:63], v[62:63], s[18:19] op_sel_hi:[1,0]
	v_pk_mul_f32 v[56:57], v[58:59], v[202:203]
	v_pk_mul_f32 v[48:49], v[48:49], s[18:19] op_sel_hi:[1,0]
	v_pk_fma_f32 v[56:57], v[62:63], v[206:207], v[56:57]
	v_mov_b32_e32 v60, 0
	v_cvt_pk_fp8_f32 v61, v56, v57 op_sel:[0,0,1]
	v_pk_mul_f32 v[52:53], v[52:53], s[18:19] op_sel_hi:[1,0]
	v_pk_mul_f32 v[56:57], v[48:49], v[204:205]
	v_pk_mul_f32 v[48:49], v[48:49], v[200:201]
	v_cvt_pk_fp8_f32 v60, v66, v67
	v_pk_fma_f32 v[56:57], v[52:53], v[200:201], v[56:57] neg_lo:[0,0,1] neg_hi:[0,0,1]
	v_pk_fma_f32 v[48:49], v[52:53], v[204:205], v[48:49]
	v_mov_b32_e32 v52, 0
	v_mov_b32_e32 v53, 0
	v_cvt_pk_fp8_f32 v52, v56, v57
	v_cvt_pk_fp8_f32 v53, v48, v49
	v_pk_mul_f32 v[78:79], v[58:59], v[206:207]
	v_pk_mul_f32 v[50:51], v[50:51], s[18:19] op_sel_hi:[1,0]
	v_pk_fma_f32 v[78:79], v[62:63], v[202:203], v[78:79] neg_lo:[0,0,1] neg_hi:[0,0,1]
	v_pk_mul_f32 v[54:55], v[54:55], s[18:19] op_sel_hi:[1,0]
	v_pk_mul_f32 v[58:59], v[50:51], v[206:207]
	v_pk_mul_f32 v[48:49], v[50:51], v[202:203]
	v_cvt_pk_fp8_f32 v60, v78, v79 op_sel:[0,0,1]
	v_pk_fma_f32 v[58:59], v[54:55], v[202:203], v[58:59] neg_lo:[0,0,1] neg_hi:[0,0,1]
	v_pk_fma_f32 v[48:49], v[54:55], v[206:207], v[48:49]
	v_bitop3_b32 v65, v65, s30, v159 bitop3:0x80
	v_cvt_pk_fp8_f32 v52, v58, v59 op_sel:[0,0,1]
	v_cvt_pk_fp8_f32 v53, v48, v49 op_sel:[0,0,1]
	v_mad_u32_u24 v48, v65, s21, v69
	v_lshl_add_u32 v48, v48, 7, v163
	buffer_store_dwordx2 v[60:61], v48, s[84:87], s28 offen
	buffer_store_dwordx2 v[52:53], v48, s[84:87], s34 offen
	v_add_u32_e32 v48, 0x90, v165
	s_and_b64 vcc, exec, s[6:7]
	v_mov_b32_e32 v69, 0
	v_mov_b32_e32 v70, 0
	v_mov_b32_e32 v71, 0
	v_mov_b32_e32 v65, 1.0
	v_mov_b32_e32 v66, 1.0
	v_mov_b32_e32 v67, 1.0
;     __device__ __forceinline__ void operator()(const f32x4 (&acc)[2][2][4][2], const Unit& u, int wr, int wc, int fr, int fq) const {
;     ...
;             for (int m = 0; m < 4; ++m) { const int row = row0 + ai * HALF + m * 16; const int si = row & 8191;
;                 const int rl = (si & ((1 << dsh) - 1)) * (8192 >> dsh) + (si >> dsh);
;                 f32x4 c = {1.f, 1.f, 1.f, 1.f}, s = {0.f, 0.f, 0.f, 0.f};
;                 if (rope) { c = __builtin_bit_cast(f32x4, __builtin_amdgcn_raw_buffer_load_b128(cs, (row * 64 + f0) * 4, 0, 0)); s = __builtin_bit_cast(f32x4, __builtin_amdgcn_raw_buffer_load_b128(sn, (row * 64 + f0) * 4, 0, 0)); }
; #pragma unroll
;                 for (int bj = 0; bj < 2; ++bj) { f32x4 v0 = acc[ai][bj][m][0] * scl, v1 = acc[ai][bj][m][1] * scl;
;                     rope_pair(v0, v1, c, s);
;                     int w0 = __builtin_amdgcn_cvt_pk_fp8_f32(v0[0], v0[1], 0, false); w0 = __builtin_amdgcn_cvt_pk_fp8_f32(v0[2], v0[3], w0, true);
;                     int w1 = __builtin_amdgcn_cvt_pk_fp8_f32(v1[0], v1[1], 0, false); w1 = __builtin_amdgcn_cvt_pk_fp8_f32(v1[2], v1[3], w1, true);
;                     typedef unsigned u32x2_t __attribute__((ext_vector_type(2)));
;                     __builtin_amdgcn_raw_buffer_store_b64((u32x2_t){(unsigned)w0, (unsigned)w1}, o, rl * 128 + cw, (int)(sbase + (unsigned)bj * (8192u * 128u)), 0); } }
.LBB0_332:
	v_and_b32_e32 v49, 0x1fdf, v48
	v_pk_mul_f32 v[40:41], v[40:41], s[18:19] op_sel_hi:[1,0]
	v_bitop3_b32 v52, v48, s30, v118 bitop3:0x80
	v_lshrrev_b32_e32 v53, s23, v49
	v_pk_mul_f32 v[44:45], v[44:45], s[18:19] op_sel_hi:[1,0]
	s_waitcnt vmcnt(14)
	v_pk_mul_f32 v[48:49], v[40:41], v[212:213]
	v_pk_mul_f32 v[40:41], v[40:41], v[208:209]
	v_pk_fma_f32 v[48:49], v[44:45], v[208:209], v[48:49] neg_lo:[0,0,1] neg_hi:[0,0,1]
	v_pk_fma_f32 v[40:41], v[44:45], v[212:213], v[40:41]
	v_mov_b32_e32 v45, 0
	v_cvt_pk_fp8_f32 v45, v40, v41
	v_pk_mul_f32 v[42:43], v[42:43], s[18:19] op_sel_hi:[1,0]
	v_pk_mul_f32 v[46:47], v[46:47], s[18:19] op_sel_hi:[1,0]
	v_pk_mul_f32 v[40:41], v[42:43], v[210:211]
	v_pk_mul_f32 v[32:33], v[32:33], s[18:19] op_sel_hi:[1,0]
	v_pk_fma_f32 v[40:41], v[46:47], v[214:215], v[40:41]
	v_mov_b32_e32 v44, 0
	v_cvt_pk_fp8_f32 v45, v40, v41 op_sel:[0,0,1]
	v_pk_mul_f32 v[36:37], v[36:37], s[18:19] op_sel_hi:[1,0]
	v_pk_mul_f32 v[40:41], v[32:33], v[212:213]
	v_pk_mul_f32 v[32:33], v[32:33], v[208:209]
	v_cvt_pk_fp8_f32 v44, v48, v49
	v_pk_fma_f32 v[40:41], v[36:37], v[208:209], v[40:41] neg_lo:[0,0,1] neg_hi:[0,0,1]
	v_pk_fma_f32 v[32:33], v[36:37], v[212:213], v[32:33]
	v_mov_b32_e32 v36, 0
	v_mov_b32_e32 v37, 0
	v_cvt_pk_fp8_f32 v36, v40, v41
	v_cvt_pk_fp8_f32 v37, v32, v33
	v_pk_mul_f32 v[50:51], v[42:43], v[214:215]
	v_pk_mul_f32 v[34:35], v[34:35], s[18:19] op_sel_hi:[1,0]
	v_pk_fma_f32 v[50:51], v[46:47], v[210:211], v[50:51] neg_lo:[0,0,1] neg_hi:[0,0,1]
	v_pk_mul_f32 v[38:39], v[38:39], s[18:19] op_sel_hi:[1,0]
	v_pk_mul_f32 v[42:43], v[34:35], v[214:215]
	v_pk_mul_f32 v[32:33], v[34:35], v[210:211]
	v_cvt_pk_fp8_f32 v44, v50, v51 op_sel:[0,0,1]
	v_pk_fma_f32 v[42:43], v[38:39], v[210:211], v[42:43] neg_lo:[0,0,1] neg_hi:[0,0,1]
	v_pk_fma_f32 v[32:33], v[38:39], v[214:215], v[32:33]
	v_cvt_pk_fp8_f32 v36, v42, v43 op_sel:[0,0,1]
	v_cvt_pk_fp8_f32 v37, v32, v33 op_sel:[0,0,1]
	v_mad_u32_u24 v32, v52, s21, v53
	v_lshl_add_u32 v32, v32, 7, v163
	buffer_store_dwordx2 v[44:45], v32, s[84:87], s28 offen
	buffer_store_dwordx2 v[36:37], v32, s[84:87], s34 offen
	v_add_u32_e32 v33, 0xa0, v165
	v_mov_b32_e32 v32, 1.0
	v_mov_b32_e32 v36, 0
	s_and_b64 vcc, exec, s[6:7]
	v_mov_b32_e32 v38, 0
	v_mov_b32_e32 v39, 0
	v_mov_b32_e32 v40, 0
	v_mov_b32_e32 v41, 0
	v_mov_b32_e32 v42, 1.0
	v_mov_b32_e32 v43, 1.0
	v_mov_b32_e32 v44, 1.0
	v_mov_b32_e32 v45, 1.0
.LBB0_334:
	v_and_b32_e32 v34, 0x1fef, v33
	v_pk_mul_f32 v[24:25], v[24:25], s[18:19] op_sel_hi:[1,0]
	v_lshrrev_b32_e32 v37, s23, v34
	v_pk_mul_f32 v[28:29], v[28:29], s[18:19] op_sel_hi:[1,0]
	s_waitcnt vmcnt(14)
	v_pk_mul_f32 v[34:35], v[24:25], v[220:221]
	v_pk_mul_f32 v[24:25], v[24:25], v[216:217]
	v_pk_fma_f32 v[34:35], v[28:29], v[216:217], v[34:35] neg_lo:[0,0,1] neg_hi:[0,0,1]
	v_pk_fma_f32 v[24:25], v[28:29], v[220:221], v[24:25]
	v_mov_b32_e32 v29, 0
	v_cvt_pk_fp8_f32 v29, v24, v25
	v_pk_mul_f32 v[26:27], v[26:27], s[18:19] op_sel_hi:[1,0]
	v_pk_mul_f32 v[30:31], v[30:31], s[18:19] op_sel_hi:[1,0]
	v_pk_mul_f32 v[24:25], v[26:27], v[218:219]
	v_pk_mul_f32 v[16:17], v[16:17], s[18:19] op_sel_hi:[1,0]
	v_pk_fma_f32 v[24:25], v[30:31], v[222:223], v[24:25]
	v_mov_b32_e32 v28, 0
	v_cvt_pk_fp8_f32 v29, v24, v25 op_sel:[0,0,1]
	v_pk_mul_f32 v[20:21], v[20:21], s[18:19] op_sel_hi:[1,0]
	v_pk_mul_f32 v[24:25], v[16:17], v[220:221]
	v_pk_mul_f32 v[16:17], v[16:17], v[216:217]
	v_cvt_pk_fp8_f32 v28, v34, v35
	v_pk_fma_f32 v[24:25], v[20:21], v[216:217], v[24:25] neg_lo:[0,0,1] neg_hi:[0,0,1]
	v_pk_fma_f32 v[16:17], v[20:21], v[220:221], v[16:17]
	v_mov_b32_e32 v20, 0
	v_mov_b32_e32 v21, 0
	v_cvt_pk_fp8_f32 v20, v24, v25
	v_cvt_pk_fp8_f32 v21, v16, v17
	v_pk_mul_f32 v[46:47], v[26:27], v[222:223]
	v_pk_mul_f32 v[18:19], v[18:19], s[18:19] op_sel_hi:[1,0]
	v_pk_fma_f32 v[46:47], v[30:31], v[218:219], v[46:47] neg_lo:[0,0,1] neg_hi:[0,0,1]
	v_pk_mul_f32 v[22:23], v[22:23], s[18:19] op_sel_hi:[1,0]
	v_pk_mul_f32 v[26:27], v[18:19], v[222:223]
	v_pk_mul_f32 v[16:17], v[18:19], v[218:219]
	v_cvt_pk_fp8_f32 v28, v46, v47 op_sel:[0,0,1]
	v_pk_fma_f32 v[26:27], v[22:23], v[218:219], v[26:27] neg_lo:[0,0,1] neg_hi:[0,0,1]
	v_pk_fma_f32 v[16:17], v[22:23], v[222:223], v[16:17]
	v_bitop3_b32 v33, v33, s30, v112 bitop3:0x80
	v_cvt_pk_fp8_f32 v20, v26, v27 op_sel:[0,0,1]
	v_cvt_pk_fp8_f32 v21, v16, v17 op_sel:[0,0,1]
	v_mad_u32_u24 v16, v33, s21, v37
	v_lshl_add_u32 v16, v16, 7, v163
	buffer_store_dwordx2 v[28:29], v16, s[84:87], s28 offen
	buffer_store_dwordx2 v[20:21], v16, s[84:87], s34 offen
	v_add_u32_e32 v16, 0xb0, v165
	s_and_b64 vcc, exec, s[6:7]
	v_mov_b32_e32 v37, 0
	v_mov_b32_e32 v38, 0
	v_mov_b32_e32 v39, 0
	v_mov_b32_e32 v33, 1.0
	v_mov_b32_e32 v34, 1.0
	v_mov_b32_e32 v35, 1.0
; #define PG8_BAR __builtin_amdgcn_s_barrier()
;     __device__ __forceinline__ void operator()(const f32x4 (&acc)[2][2][4][2], const Unit& u, int wr, int wc, int fr, int fq) const {
;     ...
;             for (int m = 0; m < 4; ++m) { const int row = row0 + ai * HALF + m * 16; const int si = row & 8191;
;                 const int rl = (si & ((1 << dsh) - 1)) * (8192 >> dsh) + (si >> dsh);
;                 f32x4 c = {1.f, 1.f, 1.f, 1.f}, s = {0.f, 0.f, 0.f, 0.f};
;                 if (rope) { c = __builtin_bit_cast(f32x4, __builtin_amdgcn_raw_buffer_load_b128(cs, (row * 64 + f0) * 4, 0, 0)); s = __builtin_bit_cast(f32x4, __builtin_amdgcn_raw_buffer_load_b128(sn, (row * 64 + f0) * 4, 0, 0)); }
; #pragma unroll
;                 for (int bj = 0; bj < 2; ++bj) { f32x4 v0 = acc[ai][bj][m][0] * scl, v1 = acc[ai][bj][m][1] * scl;
;                     rope_pair(v0, v1, c, s);
;                     int w0 = __builtin_amdgcn_cvt_pk_fp8_f32(v0[0], v0[1], 0, false); w0 = __builtin_amdgcn_cvt_pk_fp8_f32(v0[2], v0[3], w0, true);
;                     int w1 = __builtin_amdgcn_cvt_pk_fp8_f32(v1[0], v1[1], 0, false); w1 = __builtin_amdgcn_cvt_pk_fp8_f32(v1[2], v1[3], w1, true);
;                     typedef unsigned u32x2_t __attribute__((ext_vector_type(2)));
;                     __builtin_amdgcn_raw_buffer_store_b64((u32x2_t){(unsigned)w0, (unsigned)w1}, o, rl * 128 + cw, (int)(sbase + (unsigned)bj * (8192u * 128u)), 0); } }
;     ...
;         cur = nxt; cA = nA; cB = nB; ++ui;
;         if constexpr (ALIGN_EPI) { if (wr == 1) PG8_BAR; }
.LBB0_336:
	v_and_b32_e32 v17, 0x1fff, v16
	v_pk_mul_f32 v[8:9], v[8:9], s[18:19] op_sel_hi:[1,0]
	v_bitop3_b32 v20, v16, s30, v86 bitop3:0x80
	v_lshrrev_b32_e32 v21, s23, v17
	v_pk_mul_f32 v[12:13], v[12:13], s[18:19] op_sel_hi:[1,0]
	s_waitcnt vmcnt(14)
	v_pk_mul_f32 v[16:17], v[8:9], v[228:229]
	v_pk_mul_f32 v[8:9], v[8:9], v[224:225]
	v_pk_fma_f32 v[16:17], v[12:13], v[224:225], v[16:17] neg_lo:[0,0,1] neg_hi:[0,0,1]
	v_pk_fma_f32 v[8:9], v[12:13], v[228:229], v[8:9]
	v_mov_b32_e32 v13, 0
	v_cvt_pk_fp8_f32 v13, v8, v9
	v_pk_mul_f32 v[10:11], v[10:11], s[18:19] op_sel_hi:[1,0]
	v_pk_mul_f32 v[14:15], v[14:15], s[18:19] op_sel_hi:[1,0]
	v_pk_mul_f32 v[8:9], v[10:11], v[226:227]
	v_pk_mul_f32 v[0:1], v[0:1], s[18:19] op_sel_hi:[1,0]
	v_pk_fma_f32 v[8:9], v[14:15], v[230:231], v[8:9]
	v_mov_b32_e32 v12, 0
	v_cvt_pk_fp8_f32 v13, v8, v9 op_sel:[0,0,1]
	v_pk_mul_f32 v[4:5], v[4:5], s[18:19] op_sel_hi:[1,0]
	v_pk_mul_f32 v[8:9], v[0:1], v[228:229]
	v_pk_mul_f32 v[0:1], v[0:1], v[224:225]
	v_cvt_pk_fp8_f32 v12, v16, v17
	v_pk_fma_f32 v[8:9], v[4:5], v[224:225], v[8:9] neg_lo:[0,0,1] neg_hi:[0,0,1]
	v_pk_fma_f32 v[0:1], v[4:5], v[228:229], v[0:1]
	v_mov_b32_e32 v4, 0
	v_mov_b32_e32 v5, 0
	v_cvt_pk_fp8_f32 v4, v8, v9
	v_cvt_pk_fp8_f32 v5, v0, v1
	v_pk_mul_f32 v[18:19], v[10:11], v[230:231]
	v_pk_mul_f32 v[2:3], v[2:3], s[18:19] op_sel_hi:[1,0]
	v_pk_fma_f32 v[18:19], v[14:15], v[226:227], v[18:19] neg_lo:[0,0,1] neg_hi:[0,0,1]
	v_pk_mul_f32 v[6:7], v[6:7], s[18:19] op_sel_hi:[1,0]
	v_pk_mul_f32 v[10:11], v[2:3], v[230:231]
	v_pk_mul_f32 v[0:1], v[2:3], v[226:227]
	v_cvt_pk_fp8_f32 v12, v18, v19 op_sel:[0,0,1]
	v_pk_fma_f32 v[10:11], v[6:7], v[226:227], v[10:11] neg_lo:[0,0,1] neg_hi:[0,0,1]
	v_pk_fma_f32 v[0:1], v[6:7], v[230:231], v[0:1]
	v_cvt_pk_fp8_f32 v4, v10, v11 op_sel:[0,0,1]
	v_cvt_pk_fp8_f32 v5, v0, v1 op_sel:[0,0,1]
	v_mad_u32_u24 v0, v20, s21, v21
	v_lshl_add_u32 v0, v0, 7, v163
	s_andn2_b64 vcc, exec, s[4:5]
	s_mov_b64 s[4:5], -1
	buffer_store_dwordx2 v[12:13], v0, s[84:87], s28 offen
	buffer_store_dwordx2 v[4:5], v0, s[84:87], s34 offen
	s_cbranch_vccnz .LBB0_313
	s_andn2_b64 vcc, exec, s[2:3]
	s_cbranch_vccnz .LBB0_312
	s_barrier
	s_branch .LBB0_312
.Lp1e_defaults:
	v_mov_b32_e32 v168, 1.0
	v_mov_b32_e32 v169, 1.0
	v_mov_b32_e32 v170, 1.0
	v_mov_b32_e32 v171, 1.0
	v_mov_b32_e32 v172, 0
	v_mov_b32_e32 v173, 0
	v_mov_b32_e32 v174, 0
	v_mov_b32_e32 v175, 0
	v_mov_b32_e32 v176, 1.0
	v_mov_b32_e32 v177, 1.0
	v_mov_b32_e32 v178, 1.0
	v_mov_b32_e32 v179, 1.0
	v_mov_b32_e32 v180, 0
	v_mov_b32_e32 v181, 0
	v_mov_b32_e32 v182, 0
	v_mov_b32_e32 v183, 0
	v_mov_b32_e32 v184, 1.0
	v_mov_b32_e32 v185, 1.0
	v_mov_b32_e32 v186, 1.0
	v_mov_b32_e32 v187, 1.0
	v_mov_b32_e32 v188, 0
	v_mov_b32_e32 v189, 0
	v_mov_b32_e32 v190, 0
	v_mov_b32_e32 v191, 0
	v_mov_b32_e32 v192, 1.0
	v_mov_b32_e32 v193, 1.0
	v_mov_b32_e32 v194, 1.0
	v_mov_b32_e32 v195, 1.0
	v_mov_b32_e32 v196, 0
	v_mov_b32_e32 v197, 0
	v_mov_b32_e32 v198, 0
	v_mov_b32_e32 v199, 0
	v_mov_b32_e32 v200, 1.0
	v_mov_b32_e32 v201, 1.0
	v_mov_b32_e32 v202, 1.0
	v_mov_b32_e32 v203, 1.0
	v_mov_b32_e32 v204, 0
	v_mov_b32_e32 v205, 0
	v_mov_b32_e32 v206, 0
	v_mov_b32_e32 v207, 0
	v_mov_b32_e32 v208, 1.0
	v_mov_b32_e32 v209, 1.0
	v_mov_b32_e32 v210, 1.0
	v_mov_b32_e32 v211, 1.0
	v_mov_b32_e32 v212, 0
	v_mov_b32_e32 v213, 0
	v_mov_b32_e32 v214, 0
	v_mov_b32_e32 v215, 0
	v_mov_b32_e32 v216, 1.0
	v_mov_b32_e32 v217, 1.0
	v_mov_b32_e32 v218, 1.0
	v_mov_b32_e32 v219, 1.0
	v_mov_b32_e32 v220, 0
	v_mov_b32_e32 v221, 0
	v_mov_b32_e32 v222, 0
	v_mov_b32_e32 v223, 0
	v_mov_b32_e32 v224, 1.0
	v_mov_b32_e32 v225, 1.0
	v_mov_b32_e32 v226, 1.0
	v_mov_b32_e32 v227, 1.0
	v_mov_b32_e32 v228, 0
	v_mov_b32_e32 v229, 0
	v_mov_b32_e32 v230, 0
	v_mov_b32_e32 v231, 0
	s_branch .LBB0_322

; __device__ __forceinline__ unsigned cvt_pk_bf16(float lo, float hi) { unsigned r; asm volatile("v_cvt_pk_bf16_f32 %0, %1, %2" : "=v"(r) : "v"(lo), "v"(hi)); return r; }
; DI size_t a0_sub(int sq, const A0Unit& x) { return ((size_t)(((sq * 3 + x.grp) * 2 + x.b) * 16 + x.h) * 8192 + (size_t)x.r * (8192 >> (2 * x.grp))) * 128; }
; DI bf16x8 fp8x8_to_bf16(u32x2 w) {
;     typedef float f32x2_t __attribute__((ext_vector_type(2)));
;     const f32x2_t a = __builtin_amdgcn_cvt_pk_f32_fp8((int)w.x, false), b = __builtin_amdgcn_cvt_pk_f32_fp8((int)w.x, true), c = __builtin_amdgcn_cvt_pk_f32_fp8((int)w.y, false), d = __builtin_amdgcn_cvt_pk_f32_fp8((int)w.y, true);
;     u32x4 o; o.x = pg8::cvt_pk_bf16(a.x, a.y); o.y = pg8::cvt_pk_bf16(b.x, b.y); o.z = pg8::cvt_pk_bf16(c.x, c.y); o.w = pg8::cvt_pk_bf16(d.x, d.y);
;     return __builtin_bit_cast(bf16x8, o);
; DI void a0_load_q(const unsigned char* QKV, const A0Unit& x, bf16x8 (&qf)[4], int w, int n, int g4) {
;     const unsigned char* qp = QKV + a0_sub(0, x) + (size_t)(x.nb * 128 + 16 * w + n) * 128 + 8 * g4;
; #pragma unroll
;     for (int ks = 0; ks < 4; ++ks) qf[ks] = fp8x8_to_bf16(*(const u32x2*)(qp + 32 * ks));
; }
.LBB0_403:
	s_or_b64 exec, exec, s[14:15]
	s_waitcnt vmcnt(8)
	v_cvt_pk_f32_fp8_e32 v[54:55], v36
	v_cvt_pk_f32_fp8_sdwa v[56:57], v36 src0_sel:WORD_1
	v_cvt_pk_f32_fp8_e32 v[10:11], v37
	v_cvt_pk_f32_fp8_sdwa v[38:39], v37 src0_sel:WORD_1
	v_cvt_pk_bf16_f32 v36, v54, v55
	v_cvt_pk_bf16_f32 v37, v56, v57
	v_cvt_pk_bf16_f32 v39, v38, v39
	v_cvt_pk_bf16_f32 v38, v10, v11
	v_cvt_pk_f32_fp8_e32 v[54:55], v40
	v_cvt_pk_f32_fp8_sdwa v[56:57], v40 src0_sel:WORD_1
	v_cvt_pk_f32_fp8_e32 v[10:11], v41
	v_cvt_pk_f32_fp8_sdwa v[42:43], v41 src0_sel:WORD_1
	v_cvt_pk_bf16_f32 v40, v54, v55
	v_cvt_pk_bf16_f32 v41, v56, v57
	v_cvt_pk_bf16_f32 v43, v42, v43
	v_cvt_pk_bf16_f32 v42, v10, v11
	v_cvt_pk_f32_fp8_e32 v[54:55], v44
	v_cvt_pk_f32_fp8_sdwa v[56:57], v44 src0_sel:WORD_1
	v_cvt_pk_f32_fp8_e32 v[10:11], v45
	v_cvt_pk_f32_fp8_sdwa v[46:47], v45 src0_sel:WORD_1
	v_cvt_pk_bf16_f32 v44, v54, v55
	v_cvt_pk_bf16_f32 v45, v56, v57
	v_cvt_pk_bf16_f32 v47, v46, v47
	v_cvt_pk_bf16_f32 v46, v10, v11
	v_cvt_pk_f32_fp8_e32 v[54:55], v48
	v_cvt_pk_f32_fp8_sdwa v[56:57], v48 src0_sel:WORD_1
	v_cvt_pk_f32_fp8_e32 v[10:11], v49
	v_cvt_pk_f32_fp8_sdwa v[50:51], v49 src0_sel:WORD_1
	v_cvt_pk_bf16_f32 v48, v54, v55
	v_cvt_pk_bf16_f32 v49, v56, v57
	v_cvt_pk_bf16_f32 v51, v50, v51
	v_cvt_pk_bf16_f32 v50, v10, v11
	s_add_i32 s37, s37, s33
	s_andn2_b64 vcc, exec, s[94:95]
	s_mov_b32 s89, s85
	s_cbranch_vccz .LBB0_418

; #define LAS __attribute__((address_space(3)))
; DI void attn0_phase(const unsigned char* QKV, bf16_t* OG, float* LSE, LAS unsigned char* lds, int tid, int bid, int G) {
;     ...
;         f32x4 s[9];
; #pragma unroll
;         for (int tt = 0; tt < 9; ++tt) { f32x4 a = {0.f, 0.f, 0.f, 0.f};
; #pragma unroll
;             for (int ks = 0; ks < 4; ++ks) a = __builtin_amdgcn_mfma_f32_16x16x32_bf16(*(const LAS bf16x8*)(krb[ks] + tt * 4096), qf[ks], a, 0, 0, 0);
;             s[tt] = a; }
;         if (u + G < 6144) { const A0Unit xn = a0_decode(u + G); a0_load_q(QKV, xn, qf, w, n, g4); }
.LBB0_414:
	s_andn2_b64 vcc, exec, s[38:39]
	ds_read_b128 v[162:165], v120
	ds_read_b128 v[166:169], v121
	ds_read_b128 v[170:173], v122
	ds_read_b128 v[174:177], v123
	ds_read_b128 v[178:181], v120 offset:4096
	ds_read_b128 v[182:185], v121 offset:4096
	ds_read_b128 v[186:189], v122 offset:4096
	ds_read_b128 v[190:193], v123 offset:4096
	ds_read_b128 v[194:197], v120 offset:8192
	ds_read_b128 v[198:201], v121 offset:8192
	ds_read_b128 v[202:205], v122 offset:8192
	ds_read_b128 v[206:209], v123 offset:8192
	ds_read_b128 v[210:213], v120 offset:12288
	ds_read_b128 v[214:217], v121 offset:12288
	ds_read_b128 v[218:221], v122 offset:12288
	ds_read_b128 v[222:225], v123 offset:12288
	s_waitcnt lgkmcnt(15)
	v_mfma_f32_16x16x32_bf16 v[80:83], v[162:165], v[36:39], 0
	ds_read_b128 v[162:165], v120 offset:16384
	s_waitcnt lgkmcnt(15)
	v_mfma_f32_16x16x32_bf16 v[80:83], v[166:169], v[40:43], v[80:83]
	ds_read_b128 v[166:169], v121 offset:16384
	s_waitcnt lgkmcnt(15)
	v_mfma_f32_16x16x32_bf16 v[80:83], v[170:173], v[44:47], v[80:83]
	ds_read_b128 v[170:173], v122 offset:16384
	s_waitcnt lgkmcnt(15)
	v_mfma_f32_16x16x32_bf16 v[80:83], v[174:177], v[48:51], v[80:83]
	ds_read_b128 v[174:177], v123 offset:16384
	s_waitcnt lgkmcnt(15)
	v_mfma_f32_16x16x32_bf16 v[76:79], v[178:181], v[36:39], 0
	ds_read_b128 v[178:181], v120 offset:20480
	s_waitcnt lgkmcnt(15)
	v_mfma_f32_16x16x32_bf16 v[76:79], v[182:185], v[40:43], v[76:79]
	ds_read_b128 v[182:185], v121 offset:20480
	s_waitcnt lgkmcnt(15)
	v_mfma_f32_16x16x32_bf16 v[76:79], v[186:189], v[44:47], v[76:79]
	ds_read_b128 v[186:189], v122 offset:20480
	s_waitcnt lgkmcnt(15)
	v_mfma_f32_16x16x32_bf16 v[76:79], v[190:193], v[48:51], v[76:79]
	ds_read_b128 v[190:193], v123 offset:20480
	s_waitcnt lgkmcnt(15)
	v_mfma_f32_16x16x32_bf16 v[72:75], v[194:197], v[36:39], 0
	ds_read_b128 v[194:197], v120 offset:24576
	s_waitcnt lgkmcnt(15)
	v_mfma_f32_16x16x32_bf16 v[72:75], v[198:201], v[40:43], v[72:75]
	ds_read_b128 v[198:201], v121 offset:24576
	s_waitcnt lgkmcnt(15)
	v_mfma_f32_16x16x32_bf16 v[72:75], v[202:205], v[44:47], v[72:75]
	ds_read_b128 v[202:205], v122 offset:24576
	s_waitcnt lgkmcnt(15)
	v_mfma_f32_16x16x32_bf16 v[72:75], v[206:209], v[48:51], v[72:75]
	ds_read_b128 v[206:209], v123 offset:24576
	s_waitcnt lgkmcnt(15)
	v_mfma_f32_16x16x32_bf16 v[68:71], v[210:213], v[36:39], 0
	ds_read_b128 v[210:213], v120 offset:28672
	s_waitcnt lgkmcnt(15)
	v_mfma_f32_16x16x32_bf16 v[68:71], v[214:217], v[40:43], v[68:71]
	ds_read_b128 v[214:217], v121 offset:28672
	s_waitcnt lgkmcnt(15)
	v_mfma_f32_16x16x32_bf16 v[68:71], v[218:221], v[44:47], v[68:71]
	ds_read_b128 v[218:221], v122 offset:28672
	s_waitcnt lgkmcnt(15)
	v_mfma_f32_16x16x32_bf16 v[68:71], v[222:225], v[48:51], v[68:71]
	ds_read_b128 v[222:225], v123 offset:28672
	s_waitcnt lgkmcnt(15)
	v_mfma_f32_16x16x32_bf16 v[64:67], v[162:165], v[36:39], 0
	ds_read_b128 v[162:165], v120 offset:32768
	s_waitcnt lgkmcnt(15)
	v_mfma_f32_16x16x32_bf16 v[64:67], v[166:169], v[40:43], v[64:67]
	ds_read_b128 v[166:169], v121 offset:32768
	s_waitcnt lgkmcnt(15)
	v_mfma_f32_16x16x32_bf16 v[64:67], v[170:173], v[44:47], v[64:67]
	ds_read_b128 v[170:173], v122 offset:32768
	s_waitcnt lgkmcnt(15)
	v_mfma_f32_16x16x32_bf16 v[64:67], v[174:177], v[48:51], v[64:67]
	ds_read_b128 v[174:177], v123 offset:32768
	s_waitcnt lgkmcnt(15)
	v_mfma_f32_16x16x32_bf16 v[60:63], v[178:181], v[36:39], 0
	s_waitcnt lgkmcnt(14)
	v_mfma_f32_16x16x32_bf16 v[60:63], v[182:185], v[40:43], v[60:63]
	s_waitcnt lgkmcnt(13)
	v_mfma_f32_16x16x32_bf16 v[60:63], v[186:189], v[44:47], v[60:63]
	s_waitcnt lgkmcnt(12)
	v_mfma_f32_16x16x32_bf16 v[60:63], v[190:193], v[48:51], v[60:63]
	s_waitcnt lgkmcnt(11)
	v_mfma_f32_16x16x32_bf16 v[56:59], v[194:197], v[36:39], 0
	s_waitcnt lgkmcnt(10)
	v_mfma_f32_16x16x32_bf16 v[56:59], v[198:201], v[40:43], v[56:59]
	s_waitcnt lgkmcnt(9)
	v_mfma_f32_16x16x32_bf16 v[56:59], v[202:205], v[44:47], v[56:59]
	s_waitcnt lgkmcnt(8)
	v_mfma_f32_16x16x32_bf16 v[56:59], v[206:209], v[48:51], v[56:59]
	s_waitcnt lgkmcnt(7)
	v_mfma_f32_16x16x32_bf16 v[52:55], v[210:213], v[36:39], 0
	s_waitcnt lgkmcnt(6)
	v_mfma_f32_16x16x32_bf16 v[52:55], v[214:217], v[40:43], v[52:55]
	s_waitcnt lgkmcnt(5)
	v_mfma_f32_16x16x32_bf16 v[52:55], v[218:221], v[44:47], v[52:55]
	s_waitcnt lgkmcnt(4)
	v_mfma_f32_16x16x32_bf16 v[52:55], v[222:225], v[48:51], v[52:55]
	s_waitcnt lgkmcnt(3)
	v_mfma_f32_16x16x32_bf16 v[84:87], v[162:165], v[36:39], 0
	s_waitcnt lgkmcnt(2)
	v_mfma_f32_16x16x32_bf16 v[84:87], v[166:169], v[40:43], v[84:87]
	s_waitcnt lgkmcnt(1)
	v_mfma_f32_16x16x32_bf16 v[84:87], v[170:173], v[44:47], v[84:87]
	s_waitcnt lgkmcnt(0)
	v_mfma_f32_16x16x32_bf16 v[84:87], v[174:177], v[48:51], v[84:87]
	s_cbranch_vccnz .LBB0_416
	s_ashr_i32 s15, s85, 11
	s_lshl_b32 s38, s15, 1
	s_lshr_b32 s40, 64, s38
	s_bfe_u32 s14, s85, 0x60004
	s_sub_i32 s39, 6, s38
	s_add_i32 s40, s40, -1
	s_lshr_b32 s39, s14, s39
	s_and_b32 s40, s40, s14
	s_lshl_b32 s14, s15, 5
	s_lshr_b32 s15, s85, 6
	s_and_b32 s15, s15, 16
	s_and_b32 s0, s85, 15
	s_or_b32 s14, s15, s14
	s_or_b32 s14, s14, s0
	s_lshr_b32 s0, 0x2000, s38
	s_ashr_i32 s15, s14, 31
	s_mul_i32 s0, s0, s39
	s_lshl_b64 s[14:15], s[14:15], 20
	s_lshl_b32 s0, s0, 7
	v_readlane_b32 s38, v254, 25
	s_add_u32 s14, s84, s14
	v_readlane_b32 s39, v254, 26
	s_addc_u32 s15, s39, s15
	v_lshl_add_u32 v10, s40, 7, v98
	s_add_u32 s14, s14, s0
	v_ashrrev_i32_e32 v11, 31, v10
	s_addc_u32 s15, s15, 0
	v_lshlrev_b64 v[10:11], 7, v[10:11]
	v_lshl_add_u64 v[10:11], s[14:15], 0, v[10:11]
	v_lshl_add_u64 v[10:11], v[10:11], 0, v[90:91]
	global_load_dwordx2 v[36:37], v[10:11], off
	global_load_dwordx2 v[40:41], v[10:11], off offset:32
	global_load_dwordx2 v[44:45], v[10:11], off offset:64
	global_load_dwordx2 v[48:49], v[10:11], off offset:96
